# lru pass-1 conv preamble: loads of channel chunks 1-3 issued in one batch into dead VGPRs (40 loads), per-chunk counted waits
# speedup vs baseline: 1.0112x; 1.0011x over previous
.LBB0_370:
	v_add_u32_e32 v8, s85, v103
	v_add_u32_e32 v0, -2, v8
	v_cmp_lt_i32_e32 vcc, 1, v8
	v_cmp_gt_i32_e64 s[40:41], s29, v0
	s_and_b64 s[40:41], vcc, s[40:41]
	s_and_b32 s28, s83, 3
	v_cndmask_b32_e64 v0, v8, v0, s[40:41]
	v_add_u32_e32 v0, s24, v0
	s_lshl_b32 s42, s28, 7
	v_ashrrev_i32_e32 v1, 31, v0
	v_lshlrev_b64 v[0:1], 13, v[0:1]
	v_or_b32_e32 v9, s42, v105
	v_lshl_add_u64 v[10:11], s[56:57], 0, v[0:1]
	v_lshlrev_b32_e32 v16, 1, v9
	s_waitcnt vmcnt(10)
	v_lshlrev_b32_e32 v22, 2, v9
	v_lshl_add_u64 v[24:25], v[10:11], 0, v[16:17]
	global_load_dwordx4 v[0:3], v22, s[0:1] offset:16
	global_load_dwordx4 v[4:7], v22, s[0:1]
	global_load_dwordx4 v[10:13], v[24:25], off offset:3072
	v_add_u32_e32 v18, s42, v104
	v_cmp_lt_i32_e32 vcc, 0, v8
	v_cmp_ge_i32_e64 s[42:43], s29, v8
	s_and_b64 s[42:43], vcc, s[42:43]
	v_add_u32_e32 v14, s24, v8
	v_subbrev_co_u32_e64 v20, vcc, 0, v14, s[42:43]
	v_ashrrev_i32_e32 v21, 31, v20
	v_lshlrev_b64 v[20:21], 13, v[20:21]
	v_lshl_add_u64 v[20:21], s[56:57], 0, v[20:21]
	s_waitcnt vmcnt(12)
	v_lshl_add_u64 v[26:27], v[20:21], 0, v[16:17]
	v_cmp_gt_u32_e32 vcc, s29, v8
	s_mov_b64 s[44:45], 0x1000
	s_mov_b32 s84, 0
	s_ashr_i32 s86, s36, 31
	s_waitcnt vmcnt(0)
	v_cndmask_b32_e64 v9, 0, v13, s[40:41]
	v_cndmask_b32_e64 v15, 0, v12, s[40:41]
	v_cndmask_b32_e64 v19, 0, v11, s[40:41]
	v_cndmask_b32_e64 v23, 0, v10, s[40:41]
	global_load_dwordx4 v[10:13], v22, s[18:19] offset:16
	global_load_dwordx4 v[28:31], v22, s[18:19]
	global_load_dwordx4 v[32:35], v[26:27], off offset:3072
	v_lshlrev_b32_e32 v20, 16, v23
	s_waitcnt vmcnt(1)
	v_mov_b32_e32 v36, v28
	s_waitcnt vmcnt(0)
	v_cndmask_b32_e64 v38, 0, v35, s[42:43]
	v_cndmask_b32_e64 v46, 0, v34, s[42:43]
	v_cndmask_b32_e64 v47, 0, v33, s[42:43]
	v_cndmask_b32_e64 v39, 0, v32, s[42:43]
	global_load_dwordx4 v[42:45], v22, s[18:19] offset:2064
	global_load_dwordx4 v[32:35], v22, s[18:19] offset:2048
	v_lshlrev_b32_e32 v21, 16, v39
	s_waitcnt vmcnt(0)
	v_mov_b32_e32 v37, v32
	v_pk_mul_f32 v[20:21], v[36:37], v[20:21]
	v_mov_b32_e32 v32, v29
	v_add_f32_e32 v4, v4, v20
	v_add_f32_e32 v41, v4, v21
	v_and_b32_e32 v21, 0xffff0000, v39
	v_and_b32_e32 v20, 0xffff0000, v23
	v_pk_mul_f32 v[20:21], v[32:33], v[20:21]
	v_mov_b32_e32 v23, v17
	v_add_f32_e32 v4, v5, v20
	v_add_f32_e32 v40, v4, v21
	v_lshlrev_b32_e32 v5, 16, v47
	v_lshlrev_b32_e32 v4, 16, v19
	v_mov_b32_e32 v20, v30
	v_mov_b32_e32 v21, v34
	v_pk_mul_f32 v[4:5], v[20:21], v[4:5]
	v_mov_b32_e32 v34, v31
	v_add_f32_e32 v4, v6, v4
	v_add_f32_e32 v39, v4, v5
	v_and_b32_e32 v5, 0xffff0000, v47
	v_and_b32_e32 v4, 0xffff0000, v19
	v_pk_mul_f32 v[4:5], v[34:35], v[4:5]
	v_mov_b32_e32 v6, v10
	v_add_f32_e32 v4, v7, v4
	v_add_f32_e32 v37, v4, v5
	v_lshlrev_b32_e32 v5, 16, v46
	v_lshlrev_b32_e32 v4, 16, v15
	v_mov_b32_e32 v7, v42
	v_pk_mul_f32 v[4:5], v[6:7], v[4:5]
	v_mov_b32_e32 v42, v11
	v_add_f32_e32 v0, v0, v4
	v_add_f32_e32 v36, v0, v5
	v_and_b32_e32 v5, 0xffff0000, v46
	v_and_b32_e32 v4, 0xffff0000, v15
	v_pk_mul_f32 v[4:5], v[42:43], v[4:5]
	v_ashrrev_i32_e32 v15, 31, v14
	v_add_f32_e32 v0, v1, v4
	v_add_f32_e32 v35, v0, v5
	v_lshlrev_b32_e32 v1, 16, v38
	v_lshlrev_b32_e32 v0, 16, v9
	v_mov_b32_e32 v4, v12
	v_mov_b32_e32 v5, v44
	v_pk_mul_f32 v[0:1], v[4:5], v[0:1]
	v_mov_b32_e32 v44, v13
	v_add_f32_e32 v0, v2, v0
	v_add_f32_e32 v34, v0, v1
	v_and_b32_e32 v1, 0xffff0000, v38
	v_and_b32_e32 v0, 0xffff0000, v9
	v_pk_mul_f32 v[0:1], v[44:45], v[0:1]
	v_lshl_add_u64 v[30:31], s[18:19], 0, v[22:23]
	v_add_f32_e32 v0, v3, v0
	v_add_f32_e32 v19, v0, v1
	v_lshlrev_b64 v[0:1], 13, v[14:15]
	v_lshl_add_u64 v[0:1], s[56:57], 0, v[0:1]
	v_lshl_add_u64 v[20:21], v[0:1], 0, v[16:17]
	global_load_dwordx4 v[0:3], v[20:21], off offset:3072
	v_add_u32_e32 v9, 1, v8
	v_cmp_gt_i32_e64 s[46:47], s29, v9
	s_waitcnt vmcnt(0)
	v_cndmask_b32_e32 v43, 0, v1, vcc
	v_cndmask_b32_e32 v44, 0, v0, vcc
	v_lshl_add_u64 v[0:1], v[30:31], 0, s[44:45]
	v_add_co_u32_e64 v28, s[44:45], s77, v30
	v_cndmask_b32_e32 v38, 0, v3, vcc
	s_nop 0
	v_addc_co_u32_e64 v29, s[44:45], 0, v31, s[44:45]
	v_cmp_lt_i32_e64 s[44:45], -2, v8
	s_and_b64 s[44:45], s[44:45], s[46:47]
	v_cndmask_b32_e32 v42, 0, v2, vcc
	v_cndmask_b32_e64 v8, v8, v9, s[44:45]
	v_add_u32_e32 v8, s24, v8
	v_ashrrev_i32_e32 v9, 31, v8
	v_lshlrev_b64 v[8:9], 13, v[8:9]
	v_lshl_add_u64 v[8:9], s[56:57], 0, v[8:9]
	v_lshl_add_u64 v[32:33], v[8:9], 0, v[16:17]
	global_load_dwordx4 v[4:7], v[28:29], off
	s_nop 0
	global_load_dwordx4 v[0:3], v[0:1], off offset:16
	s_mov_b64 s[46:47], 0x1800
	global_load_dwordx4 v[8:11], v[32:33], off offset:3072
	v_lshlrev_b32_e32 v46, 16, v44
	v_and_b32_e32 v44, 0xffff0000, v44
	s_add_i32 s24, s85, s24
	s_or_b32 s85, s28, 12
	s_waitcnt vmcnt(2)
	v_mov_b32_e32 v48, v4
	s_waitcnt vmcnt(0)
	v_cndmask_b32_e64 v50, 0, v9, s[44:45]
	v_cndmask_b32_e64 v45, 0, v8, s[44:45]
	v_lshl_add_u64 v[8:9], v[30:31], 0, s[46:47]
	v_cndmask_b32_e64 v16, 0, v11, s[44:45]
	v_cndmask_b32_e64 v23, 0, v10, s[44:45]
	global_load_dwordx4 v[12:15], v[28:29], off offset:2048
	s_nop 0
	global_load_dwordx4 v[8:11], v[8:9], off offset:16
	global_load_dwordx4 v[52:55], v22, s[0:1] offset:48
	global_load_dwordx4 v[66:69], v22, s[0:1] offset:32
	global_load_dwordx4 v[70:73], v[24:25], off offset:3088
	global_load_dwordx4 v[74:77], v22, s[18:19] offset:48
	global_load_dwordx4 v[78:81], v22, s[18:19] offset:32
	global_load_dwordx4 v[82:85], v[26:27], off offset:3088
	global_load_dwordx4 v[86:89], v22, s[18:19] offset:2096
	global_load_dwordx4 v[90:93], v22, s[18:19] offset:2080
	global_load_dwordx4 v[94:97], v[20:21], off offset:3088
	global_load_dwordx4 v[98:101], v[28:29], off offset:32
	global_load_dwordx4 v[110:113], v[28:29], off offset:48
	global_load_dwordx4 v[114:117], v[32:33], off offset:3088
	global_load_dwordx4 v[118:121], v[28:29], off offset:2080
	global_load_dwordx4 v[122:125], v[28:29], off offset:2096
	global_load_dwordx4 v[126:129], v22, s[0:1] offset:80
	global_load_dwordx4 v[132:135], v22, s[0:1] offset:64
	global_load_dwordx4 v[136:139], v[24:25], off offset:3104
	global_load_dwordx4 v[140:143], v22, s[18:19] offset:80
	global_load_dwordx4 v[144:147], v22, s[18:19] offset:64
	global_load_dwordx4 v[148:151], v[26:27], off offset:3104
	global_load_dwordx4 v[152:155], v22, s[18:19] offset:2128
	global_load_dwordx4 v[156:159], v22, s[18:19] offset:2112
	global_load_dwordx4 v[160:163], v[20:21], off offset:3104
	global_load_dwordx4 v[164:167], v[28:29], off offset:64
	global_load_dwordx4 v[168:171], v[28:29], off offset:80
	global_load_dwordx4 v[172:175], v[32:33], off offset:3104
	global_load_dwordx4 v[176:179], v[28:29], off offset:2112
	global_load_dwordx4 v[180:183], v[28:29], off offset:2128
	global_load_dwordx4 v[184:187], v22, s[0:1] offset:112
	global_load_dwordx4 v[188:191], v22, s[0:1] offset:96
	global_load_dwordx4 v[192:195], v[24:25], off offset:3120
	global_load_dwordx4 v[196:199], v22, s[18:19] offset:112
	global_load_dwordx4 v[200:203], v22, s[18:19] offset:96
	global_load_dwordx4 v[204:207], v[26:27], off offset:3120
	global_load_dwordx4 v[224:227], v22, s[18:19] offset:2160
	global_load_dwordx4 v[228:231], v22, s[18:19] offset:2144
	global_load_dwordx4 v[232:235], v[20:21], off offset:3120
	global_load_dwordx4 v[236:239], v[28:29], off offset:96
	global_load_dwordx4 v[240:243], v[28:29], off offset:112
	global_load_dwordx4 v[244:247], v[32:33], off offset:3120
	v_lshlrev_b32_e32 v47, 16, v45
	v_and_b32_e32 v45, 0xffff0000, v45
	s_mov_b64 s[46:47], 0x1020
	s_waitcnt vmcnt(41)
	v_mov_b32_e32 v49, v12
	v_pk_mul_f32 v[46:47], v[48:49], v[46:47]
	v_mov_b32_e32 v12, v5
	v_add_f32_e32 v4, v41, v46
	v_add_f32_e32 v41, v4, v47
	v_pk_mul_f32 v[4:5], v[12:13], v[44:45]
	v_mov_b32_e32 v12, v6
	v_add_f32_e32 v4, v40, v4
	v_add_f32_e32 v40, v4, v5
	v_lshlrev_b32_e32 v5, 16, v50
	v_lshlrev_b32_e32 v4, 16, v43
	v_mov_b32_e32 v13, v14
	v_pk_mul_f32 v[4:5], v[12:13], v[4:5]
	v_mov_b32_e32 v14, v7
	v_add_f32_e32 v4, v39, v4
	v_add_f32_e32 v12, v4, v5
	v_and_b32_e32 v5, 0xffff0000, v50
	v_and_b32_e32 v4, 0xffff0000, v43
	v_pk_mul_f32 v[4:5], v[14:15], v[4:5]
	v_mov_b32_e32 v6, v0
	v_add_f32_e32 v4, v37, v4
	v_add_f32_e32 v13, v4, v5
	v_lshlrev_b32_e32 v5, 16, v23
	v_lshlrev_b32_e32 v4, 16, v42
	s_waitcnt vmcnt(40)
	v_mov_b32_e32 v7, v8
	v_pk_mul_f32 v[4:5], v[6:7], v[4:5]
	v_mov_b32_e32 v8, v1
	v_add_f32_e32 v0, v36, v4
	v_add_f32_e32 v6, v0, v5
	v_and_b32_e32 v5, 0xffff0000, v23
	v_and_b32_e32 v4, 0xffff0000, v42
	v_pk_mul_f32 v[0:1], v[8:9], v[4:5]
	v_mov_b32_e32 v4, v2
	v_add_f32_e32 v0, v35, v0
	v_add_f32_e32 v7, v0, v1
	v_lshlrev_b32_e32 v1, 16, v16
	v_lshlrev_b32_e32 v0, 16, v38
	v_mov_b32_e32 v5, v10
	v_pk_mul_f32 v[0:1], v[4:5], v[0:1]
	v_mov_b32_e32 v10, v3
	v_add_f32_e32 v0, v34, v0
	v_add_f32_e32 v4, v0, v1
	v_and_b32_e32 v1, 0xffff0000, v16
	v_and_b32_e32 v0, 0xffff0000, v38
	v_pk_mul_f32 v[0:1], v[10:11], v[0:1]
	s_nop 0
	v_add_f32_e32 v0, v19, v0
	v_add_f32_e32 v3, v0, v1
	v_cvt_pk_bf16_f32 v0, v41, v40
	v_cvt_pk_bf16_f32 v1, v12, v13
	v_cvt_pk_bf16_f32 v2, v6, v7
	v_cvt_pk_bf16_f32 v3, v4, v3
	ds_write_b128 v107, v[0:3]
	s_waitcnt vmcnt(26)
	v_mov_b32_e32 v0, v52
	v_mov_b32_e32 v1, v53
	v_mov_b32_e32 v2, v54
	v_mov_b32_e32 v3, v55
	v_mov_b32_e32 v4, v66
	v_mov_b32_e32 v5, v67
	v_mov_b32_e32 v6, v68
	v_mov_b32_e32 v7, v69
	v_mov_b32_e32 v8, v70
	v_mov_b32_e32 v9, v71
	v_mov_b32_e32 v10, v72
	v_mov_b32_e32 v11, v73
	v_cndmask_b32_e64 v16, 0, v11, s[40:41]
	v_cndmask_b32_e64 v19, 0, v10, s[40:41]
	v_cndmask_b32_e64 v23, 0, v9, s[40:41]
	v_cndmask_b32_e64 v39, 0, v8, s[40:41]
	v_mov_b32_e32 v8, v74
	v_mov_b32_e32 v9, v75
	v_mov_b32_e32 v10, v76
	v_mov_b32_e32 v11, v77
	v_mov_b32_e32 v12, v78
	v_mov_b32_e32 v13, v79
	v_mov_b32_e32 v14, v80
	v_mov_b32_e32 v15, v81
	v_mov_b32_e32 v34, v82
	v_mov_b32_e32 v35, v83
	v_mov_b32_e32 v36, v84
	v_mov_b32_e32 v37, v85
	v_mov_b32_e32 v40, v86
	v_mov_b32_e32 v41, v87
	v_mov_b32_e32 v42, v88
	v_mov_b32_e32 v43, v89
	v_mov_b32_e32 v44, v90
	v_mov_b32_e32 v45, v91
	v_mov_b32_e32 v46, v92
	v_mov_b32_e32 v47, v93
	v_cndmask_b32_e64 v51, 0, v34, s[42:43]
	v_cndmask_b32_e64 v48, 0, v37, s[42:43]
	v_cndmask_b32_e64 v49, 0, v36, s[42:43]
	v_cndmask_b32_e64 v50, 0, v35, s[42:43]
	v_lshlrev_b32_e32 v35, 16, v51
	v_lshlrev_b32_e32 v34, 16, v39
	v_mov_b32_e32 v36, v12
	v_mov_b32_e32 v37, v44
	v_pk_mul_f32 v[34:35], v[36:37], v[34:35]
	v_mov_b32_e32 v44, v13
	v_add_f32_e32 v4, v4, v34
	v_add_f32_e32 v38, v4, v35
	v_and_b32_e32 v35, 0xffff0000, v51
	v_and_b32_e32 v34, 0xffff0000, v39
	v_pk_mul_f32 v[12:13], v[44:45], v[34:35]
	s_nop 0
	v_add_f32_e32 v4, v5, v12
	v_add_f32_e32 v37, v4, v13
	v_lshlrev_b32_e32 v5, 16, v50
	v_lshlrev_b32_e32 v4, 16, v23
	v_mov_b32_e32 v12, v14
	v_mov_b32_e32 v13, v46
	v_pk_mul_f32 v[4:5], v[12:13], v[4:5]
	v_mov_b32_e32 v46, v15
	v_add_f32_e32 v4, v6, v4
	v_add_f32_e32 v36, v4, v5
	v_and_b32_e32 v5, 0xffff0000, v50
	v_and_b32_e32 v4, 0xffff0000, v23
	v_pk_mul_f32 v[4:5], v[46:47], v[4:5]
	v_mov_b32_e32 v6, v8
	v_add_f32_e32 v4, v7, v4
	v_add_f32_e32 v35, v4, v5
	v_lshlrev_b32_e32 v5, 16, v49
	v_lshlrev_b32_e32 v4, 16, v19
	v_mov_b32_e32 v7, v40
	v_pk_mul_f32 v[4:5], v[6:7], v[4:5]
	v_mov_b32_e32 v40, v9
	v_add_f32_e32 v0, v0, v4
	v_add_f32_e32 v34, v0, v5
	v_and_b32_e32 v5, 0xffff0000, v49
	v_and_b32_e32 v4, 0xffff0000, v19
	v_pk_mul_f32 v[4:5], v[40:41], v[4:5]
	s_nop 0
	v_add_f32_e32 v0, v1, v4
	v_add_f32_e32 v23, v0, v5
	v_lshlrev_b32_e32 v1, 16, v48
	v_lshlrev_b32_e32 v0, 16, v16
	v_mov_b32_e32 v4, v10
	v_mov_b32_e32 v5, v42
	v_pk_mul_f32 v[0:1], v[4:5], v[0:1]
	v_mov_b32_e32 v42, v11
	v_add_f32_e32 v0, v2, v0
	v_add_f32_e32 v19, v0, v1
	v_and_b32_e32 v1, 0xffff0000, v48
	v_and_b32_e32 v0, 0xffff0000, v16
	v_pk_mul_f32 v[0:1], v[42:43], v[0:1]
	s_nop 0
	v_add_f32_e32 v0, v3, v0
	v_add_f32_e32 v16, v0, v1
	v_mov_b32_e32 v0, v94
	v_mov_b32_e32 v1, v95
	v_mov_b32_e32 v2, v96
	v_mov_b32_e32 v3, v97
	v_cndmask_b32_e32 v46, 0, v1, vcc
	v_cndmask_b32_e32 v47, 0, v0, vcc
	v_lshl_add_u64 v[0:1], v[30:31], 0, s[46:47]
	v_cndmask_b32_e32 v44, 0, v3, vcc
	v_cndmask_b32_e32 v45, 0, v2, vcc
	v_mov_b32_e32 v4, v98
	v_mov_b32_e32 v5, v99
	v_mov_b32_e32 v6, v100
	v_mov_b32_e32 v7, v101
	s_nop 0
	v_mov_b32_e32 v0, v110
	v_mov_b32_e32 v1, v111
	v_mov_b32_e32 v2, v112
	v_mov_b32_e32 v3, v113
	s_nop 0
	v_mov_b32_e32 v8, v114
	v_mov_b32_e32 v9, v115
	v_mov_b32_e32 v10, v116
	v_mov_b32_e32 v11, v117
	s_mov_b64 s[46:47], 0x1820
	v_lshl_add_u64 v[12:13], v[30:31], 0, s[46:47]
	v_lshlrev_b32_e32 v40, 16, v47
	s_mov_b64 s[46:47], 0x1040
	v_mov_b32_e32 v42, v4
	v_cndmask_b32_e64 v48, 0, v11, s[44:45]
	v_cndmask_b32_e64 v49, 0, v10, s[44:45]
	v_cndmask_b32_e64 v50, 0, v9, s[44:45]
	v_cndmask_b32_e64 v39, 0, v8, s[44:45]
	v_mov_b32_e32 v8, v118
	v_mov_b32_e32 v9, v119
	v_mov_b32_e32 v10, v120
	v_mov_b32_e32 v11, v121
	s_nop 0
	v_mov_b32_e32 v12, v122
	v_mov_b32_e32 v13, v123
	v_mov_b32_e32 v14, v124
	v_mov_b32_e32 v15, v125
	v_lshlrev_b32_e32 v41, 16, v39
	v_and_b32_e32 v39, 0xffff0000, v39
	v_mov_b32_e32 v43, v8
	v_pk_mul_f32 v[40:41], v[42:43], v[40:41]
	v_mov_b32_e32 v8, v5
	v_add_f32_e32 v4, v38, v40
	v_and_b32_e32 v38, 0xffff0000, v47
	v_add_f32_e32 v40, v4, v41
	v_pk_mul_f32 v[4:5], v[8:9], v[38:39]
	v_mov_b32_e32 v8, v6
	v_add_f32_e32 v4, v37, v4
	v_add_f32_e32 v37, v4, v5
	v_lshlrev_b32_e32 v5, 16, v50
	v_lshlrev_b32_e32 v4, 16, v46
	v_mov_b32_e32 v9, v10
	v_pk_mul_f32 v[4:5], v[8:9], v[4:5]
	v_mov_b32_e32 v10, v7
	v_add_f32_e32 v4, v36, v4
	v_add_f32_e32 v8, v4, v5
	v_and_b32_e32 v5, 0xffff0000, v50
	v_and_b32_e32 v4, 0xffff0000, v46
	v_pk_mul_f32 v[4:5], v[10:11], v[4:5]
	v_mov_b32_e32 v6, v0
	v_add_f32_e32 v4, v35, v4
	v_add_f32_e32 v9, v4, v5
	v_lshlrev_b32_e32 v5, 16, v49
	v_lshlrev_b32_e32 v4, 16, v45
	v_mov_b32_e32 v7, v12
	v_pk_mul_f32 v[4:5], v[6:7], v[4:5]
	v_mov_b32_e32 v12, v1
	v_add_f32_e32 v0, v34, v4
	v_add_f32_e32 v6, v0, v5
	v_and_b32_e32 v5, 0xffff0000, v49
	v_and_b32_e32 v4, 0xffff0000, v45
	v_pk_mul_f32 v[0:1], v[12:13], v[4:5]
	v_mov_b32_e32 v4, v2
	v_add_f32_e32 v0, v23, v0
	v_add_f32_e32 v7, v0, v1
	v_lshlrev_b32_e32 v1, 16, v48
	v_lshlrev_b32_e32 v0, 16, v44
	v_mov_b32_e32 v5, v14
	v_pk_mul_f32 v[0:1], v[4:5], v[0:1]
	v_mov_b32_e32 v14, v3
	v_add_f32_e32 v0, v19, v0
	v_add_f32_e32 v4, v0, v1
	v_and_b32_e32 v1, 0xffff0000, v48
	v_and_b32_e32 v0, 0xffff0000, v44
	v_pk_mul_f32 v[0:1], v[14:15], v[0:1]
	s_nop 0
	v_add_f32_e32 v0, v16, v0
	v_add_f32_e32 v3, v0, v1
	v_cvt_pk_bf16_f32 v0, v40, v37
	v_cvt_pk_bf16_f32 v1, v8, v9
	v_cvt_pk_bf16_f32 v2, v6, v7
	v_cvt_pk_bf16_f32 v3, v4, v3
	ds_write_b128 v107, v[0:3] offset:16
	s_waitcnt vmcnt(12)
	v_mov_b32_e32 v0, v126
	v_mov_b32_e32 v1, v127
	v_mov_b32_e32 v2, v128
	v_mov_b32_e32 v3, v129
	v_mov_b32_e32 v4, v132
	v_mov_b32_e32 v5, v133
	v_mov_b32_e32 v6, v134
	v_mov_b32_e32 v7, v135
	v_mov_b32_e32 v8, v136
	v_mov_b32_e32 v9, v137
	v_mov_b32_e32 v10, v138
	v_mov_b32_e32 v11, v139
	v_cndmask_b32_e64 v16, 0, v11, s[40:41]
	v_cndmask_b32_e64 v19, 0, v10, s[40:41]
	v_cndmask_b32_e64 v23, 0, v9, s[40:41]
	v_cndmask_b32_e64 v39, 0, v8, s[40:41]
	v_mov_b32_e32 v8, v140
	v_mov_b32_e32 v9, v141
	v_mov_b32_e32 v10, v142
	v_mov_b32_e32 v11, v143
	v_mov_b32_e32 v12, v144
	v_mov_b32_e32 v13, v145
	v_mov_b32_e32 v14, v146
	v_mov_b32_e32 v15, v147
	v_mov_b32_e32 v34, v148
	v_mov_b32_e32 v35, v149
	v_mov_b32_e32 v36, v150
	v_mov_b32_e32 v37, v151
	v_mov_b32_e32 v40, v152
	v_mov_b32_e32 v41, v153
	v_mov_b32_e32 v42, v154
	v_mov_b32_e32 v43, v155
	v_mov_b32_e32 v44, v156
	v_mov_b32_e32 v45, v157
	v_mov_b32_e32 v46, v158
	v_mov_b32_e32 v47, v159
	v_cndmask_b32_e64 v51, 0, v34, s[42:43]
	v_cndmask_b32_e64 v48, 0, v37, s[42:43]
	v_cndmask_b32_e64 v49, 0, v36, s[42:43]
	v_cndmask_b32_e64 v50, 0, v35, s[42:43]
	v_lshlrev_b32_e32 v35, 16, v51
	v_lshlrev_b32_e32 v34, 16, v39
	v_mov_b32_e32 v36, v12
	v_mov_b32_e32 v37, v44
	v_pk_mul_f32 v[34:35], v[36:37], v[34:35]
	v_mov_b32_e32 v44, v13
	v_add_f32_e32 v4, v4, v34
	v_add_f32_e32 v38, v4, v35
	v_and_b32_e32 v35, 0xffff0000, v51
	v_and_b32_e32 v34, 0xffff0000, v39
	v_pk_mul_f32 v[12:13], v[44:45], v[34:35]
	s_nop 0
	v_add_f32_e32 v4, v5, v12
	v_add_f32_e32 v37, v4, v13
	v_lshlrev_b32_e32 v5, 16, v50
	v_lshlrev_b32_e32 v4, 16, v23
	v_mov_b32_e32 v12, v14
	v_mov_b32_e32 v13, v46
	v_pk_mul_f32 v[4:5], v[12:13], v[4:5]
	v_mov_b32_e32 v46, v15
	v_add_f32_e32 v4, v6, v4
	v_add_f32_e32 v36, v4, v5
	v_and_b32_e32 v5, 0xffff0000, v50
	v_and_b32_e32 v4, 0xffff0000, v23
	v_pk_mul_f32 v[4:5], v[46:47], v[4:5]
	v_mov_b32_e32 v6, v8
	v_add_f32_e32 v4, v7, v4
	v_add_f32_e32 v35, v4, v5
	v_lshlrev_b32_e32 v5, 16, v49
	v_lshlrev_b32_e32 v4, 16, v19
	v_mov_b32_e32 v7, v40
	v_pk_mul_f32 v[4:5], v[6:7], v[4:5]
	v_mov_b32_e32 v40, v9
	v_add_f32_e32 v0, v0, v4
	v_add_f32_e32 v34, v0, v5
	v_and_b32_e32 v5, 0xffff0000, v49
	v_and_b32_e32 v4, 0xffff0000, v19
	v_pk_mul_f32 v[4:5], v[40:41], v[4:5]
	s_nop 0
	v_add_f32_e32 v0, v1, v4
	v_add_f32_e32 v23, v0, v5
	v_lshlrev_b32_e32 v1, 16, v48
	v_lshlrev_b32_e32 v0, 16, v16
	v_mov_b32_e32 v4, v10
	v_mov_b32_e32 v5, v42
	v_pk_mul_f32 v[0:1], v[4:5], v[0:1]
	v_mov_b32_e32 v42, v11
	v_add_f32_e32 v0, v2, v0
	v_add_f32_e32 v19, v0, v1
	v_and_b32_e32 v1, 0xffff0000, v48
	v_and_b32_e32 v0, 0xffff0000, v16
	v_pk_mul_f32 v[0:1], v[42:43], v[0:1]
	s_nop 0
	v_add_f32_e32 v0, v3, v0
	v_add_f32_e32 v16, v0, v1
	v_mov_b32_e32 v0, v160
	v_mov_b32_e32 v1, v161
	v_mov_b32_e32 v2, v162
	v_mov_b32_e32 v3, v163
	v_cndmask_b32_e32 v46, 0, v1, vcc
	v_cndmask_b32_e32 v47, 0, v0, vcc
	v_lshl_add_u64 v[0:1], v[30:31], 0, s[46:47]
	v_cndmask_b32_e32 v44, 0, v3, vcc
	v_cndmask_b32_e32 v45, 0, v2, vcc
	v_mov_b32_e32 v4, v164
	v_mov_b32_e32 v5, v165
	v_mov_b32_e32 v6, v166
	v_mov_b32_e32 v7, v167
	s_nop 0
	v_mov_b32_e32 v0, v168
	v_mov_b32_e32 v1, v169
	v_mov_b32_e32 v2, v170
	v_mov_b32_e32 v3, v171
	s_nop 0
	v_mov_b32_e32 v8, v172
	v_mov_b32_e32 v9, v173
	v_mov_b32_e32 v10, v174
	v_mov_b32_e32 v11, v175
	s_mov_b64 s[46:47], 0x1840
	v_lshl_add_u64 v[12:13], v[30:31], 0, s[46:47]
	v_lshlrev_b32_e32 v40, 16, v47
	s_ashr_i32 s46, s37, 31
	s_or_b32 s47, s28, 4
	s_mov_b64 s[28:29], 0
	v_mov_b32_e32 v42, v4
	v_cndmask_b32_e64 v48, 0, v11, s[44:45]
	v_cndmask_b32_e64 v49, 0, v10, s[44:45]
	v_cndmask_b32_e64 v50, 0, v9, s[44:45]
	v_cndmask_b32_e64 v39, 0, v8, s[44:45]
	v_mov_b32_e32 v8, v176
	v_mov_b32_e32 v9, v177
	v_mov_b32_e32 v10, v178
	v_mov_b32_e32 v11, v179
	s_nop 0
	v_mov_b32_e32 v12, v180
	v_mov_b32_e32 v13, v181
	v_mov_b32_e32 v14, v182
	v_mov_b32_e32 v15, v183
	v_lshlrev_b32_e32 v41, 16, v39
	v_and_b32_e32 v39, 0xffff0000, v39
	v_mov_b32_e32 v43, v8
	v_pk_mul_f32 v[40:41], v[42:43], v[40:41]
	v_mov_b32_e32 v8, v5
	v_add_f32_e32 v4, v38, v40
	v_and_b32_e32 v38, 0xffff0000, v47
	v_add_f32_e32 v40, v4, v41
	v_pk_mul_f32 v[4:5], v[8:9], v[38:39]
	v_mov_b32_e32 v8, v6
	v_add_f32_e32 v4, v37, v4
	v_add_f32_e32 v37, v4, v5
	v_lshlrev_b32_e32 v5, 16, v50
	v_lshlrev_b32_e32 v4, 16, v46
	v_mov_b32_e32 v9, v10
	v_pk_mul_f32 v[4:5], v[8:9], v[4:5]
	v_mov_b32_e32 v10, v7
	v_add_f32_e32 v4, v36, v4
	v_add_f32_e32 v8, v4, v5
	v_and_b32_e32 v5, 0xffff0000, v50
	v_and_b32_e32 v4, 0xffff0000, v46
	v_pk_mul_f32 v[4:5], v[10:11], v[4:5]
	v_mov_b32_e32 v6, v0
	v_add_f32_e32 v4, v35, v4
	v_add_f32_e32 v9, v4, v5
	v_lshlrev_b32_e32 v5, 16, v49
	v_lshlrev_b32_e32 v4, 16, v45
	v_mov_b32_e32 v7, v12
	v_pk_mul_f32 v[4:5], v[6:7], v[4:5]
	v_mov_b32_e32 v12, v1
	v_add_f32_e32 v0, v34, v4
	v_add_f32_e32 v6, v0, v5
	v_and_b32_e32 v5, 0xffff0000, v49
	v_and_b32_e32 v4, 0xffff0000, v45
	v_pk_mul_f32 v[0:1], v[12:13], v[4:5]
	v_mov_b32_e32 v4, v2
	v_add_f32_e32 v0, v23, v0
	v_add_f32_e32 v7, v0, v1
	v_lshlrev_b32_e32 v1, 16, v48
	v_lshlrev_b32_e32 v0, 16, v44
	v_mov_b32_e32 v5, v14
	v_pk_mul_f32 v[0:1], v[4:5], v[0:1]
	v_mov_b32_e32 v14, v3
	v_add_f32_e32 v0, v19, v0
	v_add_f32_e32 v4, v0, v1
	v_and_b32_e32 v1, 0xffff0000, v48
	v_and_b32_e32 v0, 0xffff0000, v44
	v_pk_mul_f32 v[0:1], v[14:15], v[0:1]
	s_nop 0
	v_add_f32_e32 v0, v16, v0
	v_add_f32_e32 v3, v0, v1
	v_cvt_pk_bf16_f32 v0, v40, v37
	v_cvt_pk_bf16_f32 v1, v8, v9
	v_cvt_pk_bf16_f32 v2, v6, v7
	v_cvt_pk_bf16_f32 v3, v4, v3
	ds_write_b128 v107, v[0:3] offset:32
	s_waitcnt vmcnt(0)
	v_mov_b32_e32 v0, v184
	v_mov_b32_e32 v1, v185
	v_mov_b32_e32 v2, v186
	v_mov_b32_e32 v3, v187
	v_mov_b32_e32 v4, v188
	v_mov_b32_e32 v5, v189
	v_mov_b32_e32 v6, v190
	v_mov_b32_e32 v7, v191
	v_mov_b32_e32 v8, v192
	v_mov_b32_e32 v9, v193
	v_mov_b32_e32 v10, v194
	v_mov_b32_e32 v11, v195
	s_waitcnt vmcnt(0)
	v_cndmask_b32_e64 v16, 0, v11, s[40:41]
	v_cndmask_b32_e64 v19, 0, v10, s[40:41]
	v_cndmask_b32_e64 v42, 0, v9, s[40:41]
	v_cndmask_b32_e64 v43, 0, v8, s[40:41]
	v_mov_b32_e32 v8, v196
	v_mov_b32_e32 v9, v197
	v_mov_b32_e32 v10, v198
	v_mov_b32_e32 v11, v199
	v_mov_b32_e32 v12, v200
	v_mov_b32_e32 v13, v201
	v_mov_b32_e32 v14, v202
	v_mov_b32_e32 v15, v203
	s_nop 0
	v_mov_b32_e32 v24, v204
	v_mov_b32_e32 v25, v205
	v_mov_b32_e32 v26, v206
	v_mov_b32_e32 v27, v207
	s_nop 0
	v_mov_b32_e32 v34, v224
	v_mov_b32_e32 v35, v225
	v_mov_b32_e32 v36, v226
	v_mov_b32_e32 v37, v227
	v_mov_b32_e32 v38, v228
	v_mov_b32_e32 v39, v229
	v_mov_b32_e32 v40, v230
	v_mov_b32_e32 v41, v231
	v_lshlrev_b32_e32 v22, 16, v43
	s_mov_b64 s[40:41], 0x1060
	s_waitcnt vmcnt(2)
	v_cndmask_b32_e64 v45, 0, v26, s[42:43]
	v_cndmask_b32_e64 v26, 0, v24, s[42:43]
	v_cndmask_b32_e64 v46, 0, v25, s[42:43]
	v_lshlrev_b32_e32 v23, 16, v26
	v_mov_b32_e32 v24, v12
	s_waitcnt vmcnt(0)
	v_mov_b32_e32 v25, v38
	v_pk_mul_f32 v[22:23], v[24:25], v[22:23]
	v_cndmask_b32_e64 v44, 0, v27, s[42:43]
	v_add_f32_e32 v4, v4, v22
	v_add_f32_e32 v27, v4, v23
	v_and_b32_e32 v23, 0xffff0000, v26
	v_and_b32_e32 v22, 0xffff0000, v43
	v_mov_b32_e32 v38, v13
	v_pk_mul_f32 v[12:13], v[38:39], v[22:23]
	s_mov_b64 s[42:43], -1
	v_add_f32_e32 v4, v5, v12
	v_add_f32_e32 v26, v4, v13
	v_lshlrev_b32_e32 v5, 16, v46
	v_lshlrev_b32_e32 v4, 16, v42
	v_mov_b32_e32 v12, v14
	v_mov_b32_e32 v13, v40
	v_pk_mul_f32 v[4:5], v[12:13], v[4:5]
	v_mov_b32_e32 v40, v15
	v_add_f32_e32 v4, v6, v4
	v_add_f32_e32 v25, v4, v5
	v_and_b32_e32 v5, 0xffff0000, v46
	v_and_b32_e32 v4, 0xffff0000, v42
	v_pk_mul_f32 v[4:5], v[40:41], v[4:5]
	v_mov_b32_e32 v6, v8
	v_add_f32_e32 v4, v7, v4
	v_add_f32_e32 v24, v4, v5
	v_lshlrev_b32_e32 v5, 16, v45
	v_lshlrev_b32_e32 v4, 16, v19
	v_mov_b32_e32 v7, v34
	v_pk_mul_f32 v[4:5], v[6:7], v[4:5]
	v_mov_b32_e32 v34, v9
	v_add_f32_e32 v0, v0, v4
	v_add_f32_e32 v23, v0, v5
	v_and_b32_e32 v5, 0xffff0000, v45
	v_and_b32_e32 v4, 0xffff0000, v19
	v_pk_mul_f32 v[4:5], v[34:35], v[4:5]
	s_nop 0
	v_add_f32_e32 v0, v1, v4
	v_add_f32_e32 v22, v0, v5
	v_lshlrev_b32_e32 v1, 16, v44
	v_lshlrev_b32_e32 v0, 16, v16
	v_mov_b32_e32 v4, v10
	v_mov_b32_e32 v5, v36
	v_pk_mul_f32 v[0:1], v[4:5], v[0:1]
	v_mov_b32_e32 v36, v11
	v_add_f32_e32 v0, v2, v0
	v_add_f32_e32 v19, v0, v1
	v_and_b32_e32 v1, 0xffff0000, v44
	v_and_b32_e32 v0, 0xffff0000, v16
	v_pk_mul_f32 v[0:1], v[36:37], v[0:1]
	s_nop 0
	v_add_f32_e32 v0, v3, v0
	v_add_f32_e32 v16, v0, v1
	v_mov_b32_e32 v0, v232
	v_mov_b32_e32 v1, v233
	v_mov_b32_e32 v2, v234
	v_mov_b32_e32 v3, v235
	s_waitcnt vmcnt(0)
	v_cndmask_b32_e32 v36, 0, v1, vcc
	v_cndmask_b32_e32 v37, 0, v0, vcc
	v_lshl_add_u64 v[0:1], v[30:31], 0, s[40:41]
	v_cndmask_b32_e32 v34, 0, v3, vcc
	v_cndmask_b32_e32 v35, 0, v2, vcc
	v_mov_b32_e32 v4, v236
	v_mov_b32_e32 v5, v237
	v_mov_b32_e32 v6, v238
	v_mov_b32_e32 v7, v239
	s_nop 0
	v_mov_b32_e32 v0, v240
	v_mov_b32_e32 v1, v241
	v_mov_b32_e32 v2, v242
	v_mov_b32_e32 v3, v243
	s_nop 0
	v_mov_b32_e32 v8, v244
	v_mov_b32_e32 v9, v245
	v_mov_b32_e32 v10, v246
	v_mov_b32_e32 v11, v247
	s_mov_b64 s[40:41], 0x1860
	v_lshl_add_u64 v[12:13], v[30:31], 0, s[40:41]
	v_lshlrev_b32_e32 v20, 16, v37
	s_waitcnt vmcnt(0)
	v_cndmask_b32_e64 v32, 0, v11, s[44:45]
	v_cndmask_b32_e64 v33, 0, v10, s[44:45]
	v_cndmask_b32_e64 v38, 0, v9, s[44:45]
	v_cndmask_b32_e64 v39, 0, v8, s[44:45]
	global_load_dwordx4 v[8:11], v[28:29], off offset:2144
	s_nop 0
	global_load_dwordx4 v[12:15], v[12:13], off offset:16
	v_lshlrev_b32_e32 v21, 16, v39
	v_mov_b32_e32 v28, v4
	s_waitcnt vmcnt(1)
	v_mov_b32_e32 v29, v8
	v_pk_mul_f32 v[20:21], v[28:29], v[20:21]
	v_mov_b32_e32 v8, v5
	v_add_f32_e32 v4, v27, v20
	v_add_f32_e32 v27, v4, v21
	v_and_b32_e32 v21, 0xffff0000, v39
	v_and_b32_e32 v20, 0xffff0000, v37
	v_pk_mul_f32 v[4:5], v[8:9], v[20:21]
	v_mov_b32_e32 v8, v6
	v_add_f32_e32 v4, v26, v4
	v_add_f32_e32 v20, v4, v5
	v_lshlrev_b32_e32 v5, 16, v38
	v_lshlrev_b32_e32 v4, 16, v36
	v_mov_b32_e32 v9, v10
	v_pk_mul_f32 v[4:5], v[8:9], v[4:5]
	v_mov_b32_e32 v10, v7
	v_add_f32_e32 v4, v25, v4
	v_add_f32_e32 v8, v4, v5
	v_and_b32_e32 v5, 0xffff0000, v38
	v_and_b32_e32 v4, 0xffff0000, v36
	v_pk_mul_f32 v[4:5], v[10:11], v[4:5]
	v_mov_b32_e32 v6, v0
	v_add_f32_e32 v4, v24, v4
	v_add_f32_e32 v9, v4, v5
	v_lshlrev_b32_e32 v5, 16, v33
	v_lshlrev_b32_e32 v4, 16, v35
	s_waitcnt vmcnt(0)
	v_mov_b32_e32 v7, v12
	v_pk_mul_f32 v[4:5], v[6:7], v[4:5]
	v_mov_b32_e32 v12, v1
	v_add_f32_e32 v0, v23, v4
	v_add_f32_e32 v6, v0, v5
	v_and_b32_e32 v5, 0xffff0000, v33
	v_and_b32_e32 v4, 0xffff0000, v35
	v_pk_mul_f32 v[0:1], v[12:13], v[4:5]
	v_mov_b32_e32 v4, v2
	v_add_f32_e32 v0, v22, v0
	v_add_f32_e32 v7, v0, v1
	v_lshlrev_b32_e32 v1, 16, v32
	v_lshlrev_b32_e32 v0, 16, v34
	v_mov_b32_e32 v5, v14
	v_pk_mul_f32 v[0:1], v[4:5], v[0:1]
	v_mov_b32_e32 v14, v3
	v_add_f32_e32 v0, v19, v0
	v_add_f32_e32 v4, v0, v1
	v_and_b32_e32 v1, 0xffff0000, v32
	v_and_b32_e32 v0, 0xffff0000, v34
	v_pk_mul_f32 v[0:1], v[14:15], v[0:1]
	v_ashrrev_i32_e32 v19, 31, v18
	v_add_f32_e32 v0, v16, v0
	v_add_f32_e32 v3, v0, v1
	v_cvt_pk_bf16_f32 v0, v27, v20
	v_cvt_pk_bf16_f32 v1, v8, v9
	v_cvt_pk_bf16_f32 v2, v6, v7
	v_cvt_pk_bf16_f32 v3, v4, v3
	ds_write_b128 v107, v[0:3] offset:48
	v_add_u32_e32 v0, s24, v106
	v_ashrrev_i32_e32 v60, 2, v0
	v_ashrrev_i32_e32 v61, 31, v60
	v_add_u32_e32 v16, s26, v18
	v_lshl_add_u64 v[62:63], v[18:19], 4, s[52:53]
	v_lshl_add_u64 v[64:65], v[18:19], 3, s[22:23]
	s_waitcnt lgkmcnt(0)
	s_barrier
	s_branch .LBB0_372
